# phase-0 transposes: 2x4 tile-block item remap applied to all seven weight matrices; plus phase-0 nt loads
# speedup vs baseline: 1.0080x; 1.0080x over previous
; #define LAS __attribute__((address_space(3)))
; #define SCHED_FENCE() __builtin_amdgcn_sched_barrier(0)
; __device__ __forceinline__ void transpose_item(const float* W, int K, int N, bf16_t* WT, int kb, int nbd, int src0, LAS float* scr, int lane, const float* gk = nullptr) {
;     const int k0 = kb * 64;
;     const float* wp = W + (size_t)(k0 + (lane >> 4)) * N + src0 + (lane & 15) * 4;
;     f32x4 v[16];
; #pragma unroll
;     for (int i = 0; i < 16; ++i) v[i] = *(const f32x4*)(wp + (size_t)(4 * i) * N);
;     SCHED_FENCE();
; #pragma unroll
;     for (int i = 0; i < 16; ++i) { if (gk) v[i] = v[i] * gk[k0 + 4 * i + (lane >> 4)];
;         LAS float* s = scr + (4 * i + (lane >> 4)) * 65 + (lane & 15) * 4; s[0] = v[i].x; s[1] = v[i].y; s[2] = v[i].z; s[3] = v[i].w; }
; __global__ void __launch_bounds__(512, 2) fwd_kernel(Args a) {
;     ...
;             for (int it = gw; it < NITEMS; it += ngw) {
;                 int r = it;
;                 if (r < I_GU) { const int nb = r % 176; transpose_item(P.in[3], DM, NGU, (bf16_t*)(ws + WS_WGU1), r / 176, nb, map_gu(nb), scr, lane, P.in[2]); continue; } r -= I_GU;
;                 if (r < I_GU) { const int nb = r % 176; transpose_item(P.in[21], DM, NGU, (bf16_t*)(ws + WS_WGU2), r / 176, nb, map_gu(nb), scr, lane, P.in[20]); continue; } r -= I_GU;
;                 if (r < I_D) { const int nb = r % 32; transpose_item(P.in[4], DFF, DM, (bf16_t*)(ws + WS_WD1), r / 32, nb, nb * 64, scr, lane); continue; } r -= I_D;
;                 if (r < I_D) { const int nb = r % 32; transpose_item(P.in[22], DFF, DM, (bf16_t*)(ws + WS_WD2), r / 32, nb, nb * 64, scr, lane); continue; } r -= I_D;
;                 if (r < I_IN) { const int nb = r % 72; transpose_item(P.in[8], DM, 4608, (bf16_t*)(ws + WS_WIN), r / 72, nb, map_win(nb), scr, lane, P.in[6]); continue; } r -= I_IN;
;                 if (r < I_MKV) { const int nb = r % 16; transpose_item(P.in[9], DM, 1024, (bf16_t*)(ws + WS_WMKV), r / 16, nb, nb * 64, scr, lane); continue; } r -= I_MKV;
;                 { const int nb = r % 32; transpose_item(P.in[18], DM, DM, (bf16_t*)(ws + WS_WOUT), r / 32, nb, nb * 64, scr, lane); }
.LBB0_258:
	s_mov_b32 s100, s28
	s_cmpk_gt_u32 s28, 0x2bff
	s_cbranch_scc1 .Lm_wd
	s_cmpk_gt_u32 s28, 0x15ff
	s_cselect_b32 s7, 0x1600, 0
	s_movk_i32 s6, 88
	s_mov_b32 s101, 0x2e8c
	s_branch .Lm_go
.Lm_wd:
	s_cmpk_gt_u32 s28, 0x41ff
	s_cbranch_scc1 .Lm_win
	s_movk_i32 s7, 0x2c00
	s_cmpk_gt_u32 s28, 0x36ff
	s_cselect_b32 s7, 0x3700, s7
	s_movk_i32 s6, 16
	s_mov_b32 s101, 0x10000
	s_branch .Lm_go
.Lm_win:
	s_cmpk_gt_u32 s28, 0x4aff
	s_cbranch_scc1 .Lm_mkv
	s_movk_i32 s7, 0x4200
	s_movk_i32 s6, 36
	s_mov_b32 s101, 0x71c8
	s_branch .Lm_go
.Lm_mkv:
	s_cmpk_gt_u32 s28, 0x4cff
	s_cbranch_scc1 .Lm_wout
	s_movk_i32 s7, 0x4b00
	s_movk_i32 s6, 8
	s_mov_b32 s101, 0x20000
	s_branch .Lm_go
.Lm_wout:
	s_movk_i32 s7, 0x4d00
	s_movk_i32 s6, 16
	s_mov_b32 s101, 0x10000
.Lm_go:
	s_sub_u32 s8, s28, s7
	s_and_b32 s9, s8, 7
	s_lshr_b32 s8, s8, 3
	s_mul_i32 s28, s8, s101
	s_lshr_b32 s28, s28, 20
	s_mul_i32 s101, s28, s6
	s_sub_u32 s8, s8, s101
	s_lshl_b32 s8, s8, 1
	s_and_b32 s101, s9, 1
	s_add_u32 s8, s8, s101
	s_lshl_b32 s28, s28, 2
	s_lshr_b32 s9, s9, 1
	s_add_u32 s28, s28, s9
	s_lshl_b32 s6, s6, 1
	s_mul_i32 s28, s28, s6
	s_add_u32 s28, s28, s8
	s_add_u32 s28, s28, s7
	s_lshl_b32 s10, s28, 5
	s_lshl_b32 s23, s28, 6
	s_lshl_b32 s13, s28, 1
	s_lshl_b32 s19, s28, 2
	s_cmpk_gt_i32 s28, 0x15ff
	s_mov_b64 s[6:7], -1
	s_cbranch_scc0 .LBB0_337
	s_cmpk_gt_u32 s28, 0x2bff
	s_cbranch_scc0 .LBB0_310
	s_cmpk_gt_u32 s28, 0x36ff
	s_cbranch_scc0 .LBB0_307
	s_cmpk_gt_u32 s28, 0x41ff
	s_cbranch_scc0 .LBB0_304
	s_cmpk_gt_u32 s28, 0x4aff
	s_cbranch_scc0 .LBB0_268
	s_cmpk_gt_u32 s28, 0x4cff
	s_cbranch_scc0 .LBB0_265
	s_load_dwordx2 s[30:31], s[40:41], 0x90
	s_and_b32 s6, s13, 0x7fffffc0
	s_add_i32 s6, s6, 0xffff6600
	v_or_b32_e32 v144, s6, v92
	s_and_b32 s8, s23, 0x7c0
	v_lshlrev_b64 v[0:1], 13, v[144:145]
	s_waitcnt lgkmcnt(0)
	v_lshl_add_u64 v[0:1], s[30:31], 0, v[0:1]
	s_lshl_b32 s74, s8, 2
	v_lshl_add_u64 v[0:1], v[0:1], 0, s[74:75]
	v_lshlrev_b32_e32 v144, 2, v70
	v_lshl_add_u64 v[56:57], v[0:1], 0, v[144:145]
	v_add_co_u32_e32 v4, vcc, 0x8000, v56
	s_mov_b32 s0, 0x18000
	s_nop 0
	v_addc_co_u32_e32 v5, vcc, 0, v57, vcc
	v_add_co_u32_e32 v8, vcc, s47, v56
	global_load_dwordx4 v[0:3], v[56:57], off nt
	s_nop 0
	global_load_dwordx4 v[4:7], v[4:5], off nt
	v_addc_co_u32_e32 v9, vcc, 0, v57, vcc
	v_add_co_u32_e32 v12, vcc, s0, v56
	s_mov_b32 s0, 0x48000
	s_nop 0
	v_addc_co_u32_e32 v13, vcc, 0, v57, vcc
	v_add_co_u32_e32 v16, vcc, 0x20000, v56
	global_load_dwordx4 v[8:11], v[8:9], off nt
	s_nop 0
	global_load_dwordx4 v[12:15], v[12:13], off nt
	v_addc_co_u32_e32 v17, vcc, 0, v57, vcc
	v_add_co_u32_e32 v20, vcc, 0x28000, v56
	s_nop 1
	v_addc_co_u32_e32 v21, vcc, 0, v57, vcc
	v_add_co_u32_e32 v24, vcc, s3, v56
	global_load_dwordx4 v[16:19], v[16:17], off nt
	s_nop 0
	global_load_dwordx4 v[20:23], v[20:21], off nt
	v_addc_co_u32_e32 v25, vcc, 0, v57, vcc
	v_add_co_u32_e32 v28, vcc, 0x38000, v56
	s_nop 1
	v_addc_co_u32_e32 v29, vcc, 0, v57, vcc
	v_add_co_u32_e32 v32, vcc, s21, v56
	global_load_dwordx4 v[24:27], v[24:25], off nt
	s_nop 0
	global_load_dwordx4 v[28:31], v[28:29], off nt
	v_addc_co_u32_e32 v33, vcc, 0, v57, vcc
	v_add_co_u32_e32 v36, vcc, s0, v56
	s_mov_b32 s0, 0x58000
	s_nop 0
	v_addc_co_u32_e32 v37, vcc, 0, v57, vcc
	v_add_co_u32_e32 v40, vcc, s20, v56
	global_load_dwordx4 v[32:35], v[32:33], off nt
	s_nop 0
	global_load_dwordx4 v[36:39], v[36:37], off nt
	v_addc_co_u32_e32 v41, vcc, 0, v57, vcc
	v_add_co_u32_e32 v44, vcc, s0, v56
	s_mov_b32 s0, 0x68000
	s_nop 0
	v_addc_co_u32_e32 v45, vcc, 0, v57, vcc
	v_add_co_u32_e32 v48, vcc, s26, v56
	global_load_dwordx4 v[40:43], v[40:41], off nt
	s_nop 0
	global_load_dwordx4 v[44:47], v[44:45], off nt
	v_addc_co_u32_e32 v49, vcc, 0, v57, vcc
	v_add_co_u32_e32 v52, vcc, s0, v56
	s_mov_b32 s0, 0x78000
	s_nop 0
	v_addc_co_u32_e32 v53, vcc, 0, v57, vcc
	v_add_co_u32_e32 v58, vcc, s48, v56
	global_load_dwordx4 v[48:51], v[48:49], off nt
	s_nop 0
	global_load_dwordx4 v[52:55], v[52:53], off nt
	v_addc_co_u32_e32 v59, vcc, 0, v57, vcc
	v_add_co_u32_e32 v60, vcc, s0, v56
	s_nop 1
	v_addc_co_u32_e32 v61, vcc, 0, v57, vcc
	global_load_dwordx4 v[56:59], v[58:59], off nt
	s_nop 0
	global_load_dwordx4 v[60:63], v[60:61], off nt
	s_waitcnt vmcnt(15)
	ds_write2_b32 v93, v0, v1 offset1:1
	ds_write2_b32 v93, v2, v3 offset0:2 offset1:3
	v_add_u32_e32 v0, 0x410, v93
	s_waitcnt vmcnt(14)
	ds_write2_b32 v0, v4, v5 offset1:1
	v_add_u32_e32 v0, 0x418, v93
	ds_write2_b32 v0, v6, v7 offset1:1
	v_add_u32_e32 v0, 0x820, v93
	s_waitcnt vmcnt(13)
	ds_write2_b32 v0, v8, v9 offset1:1
	v_add_u32_e32 v0, 0x828, v93
	ds_write2_b32 v0, v10, v11 offset1:1
	v_add_u32_e32 v0, 0xc30, v93
	s_waitcnt vmcnt(12)
	ds_write2_b32 v0, v12, v13 offset1:1
	v_add_u32_e32 v0, 0xc38, v93
	ds_write2_b32 v0, v14, v15 offset1:1
	v_add_u32_e32 v0, 0x1040, v93
	s_waitcnt vmcnt(11)
	ds_write2_b32 v0, v16, v17 offset1:1
	v_add_u32_e32 v0, 0x1048, v93
	ds_write2_b32 v0, v18, v19 offset1:1
	v_add_u32_e32 v0, 0x1450, v93
	s_waitcnt vmcnt(10)
	ds_write2_b32 v0, v20, v21 offset1:1
	v_add_u32_e32 v0, 0x1458, v93
	ds_write2_b32 v0, v22, v23 offset1:1
	v_add_u32_e32 v0, 0x1860, v93
	s_waitcnt vmcnt(9)
	ds_write2_b32 v0, v24, v25 offset1:1
	v_add_u32_e32 v0, 0x1868, v93
	ds_write2_b32 v0, v26, v27 offset1:1
	v_add_u32_e32 v0, 0x1c70, v93
	s_waitcnt vmcnt(8)
	ds_write2_b32 v0, v28, v29 offset1:1
	v_add_u32_e32 v0, 0x1c78, v93
	ds_write2_b32 v0, v30, v31 offset1:1
	v_add_u32_e32 v0, 0x2080, v93
	s_waitcnt vmcnt(7)
; #define LAS __attribute__((address_space(3)))
; __device__ __forceinline__ unsigned pk2(float lo, float hi) { unsigned r; asm("v_cvt_pk_bf16_f32 %0, %1, %2" : "=v"(r) : "v"(lo), "v"(hi)); return r; }
; __device__ __forceinline__ void transpose_item(const float* W, int K, int N, bf16_t* WT, int kb, int nbd, int src0, LAS float* scr, int lane, const float* gk = nullptr) {
;     ...
;         LAS float* s = scr + (4 * i + (lane >> 4)) * 65 + (lane & 15) * 4; s[0] = v[i].x; s[1] = v[i].y; s[2] = v[i].z; s[3] = v[i].w; }
;     const int c = lane & 7;
; #pragma unroll
;     for (int jj = 0; jj < 8; ++jj) {
;         const int n = (lane >> 3) + 8 * jj; const LAS float* s = scr + (8 * c) * 65 + n;
;         u32x4 o; o.x = pk2(s[0], s[65]); o.y = pk2(s[2 * 65], s[3 * 65]); o.z = pk2(s[4 * 65], s[5 * 65]); o.w = pk2(s[6 * 65], s[7 * 65]);
;         *(u32x4*)(WT + (size_t)(nbd * 64 + n) * K + k0 + 8 * c) = o;
;     }
	ds_write2_b32 v0, v32, v33 offset1:1
	v_add_u32_e32 v0, 0x2088, v93
	ds_write2_b32 v0, v34, v35 offset1:1
	v_add_u32_e32 v0, 0x2490, v93
	s_waitcnt vmcnt(6)
	ds_write2_b32 v0, v36, v37 offset1:1
	v_add_u32_e32 v0, 0x2498, v93
	ds_write2_b32 v0, v38, v39 offset1:1
	v_add_u32_e32 v0, 0x28a0, v93
	s_waitcnt vmcnt(5)
	ds_write2_b32 v0, v40, v41 offset1:1
	v_add_u32_e32 v0, 0x28a8, v93
	ds_write2_b32 v0, v42, v43 offset1:1
	v_add_u32_e32 v0, 0x2cb0, v93
	s_waitcnt vmcnt(4)
	ds_write2_b32 v0, v44, v45 offset1:1
	v_add_u32_e32 v0, 0x2cb8, v93
	ds_write2_b32 v0, v46, v47 offset1:1
	v_add_u32_e32 v0, 0x30c0, v93
	s_waitcnt vmcnt(3)
	ds_write2_b32 v0, v48, v49 offset1:1
	v_add_u32_e32 v0, 0x30c8, v93
	ds_write2_b32 v0, v50, v51 offset1:1
	v_add_u32_e32 v0, 0x34d0, v93
	s_waitcnt vmcnt(2)
	ds_write2_b32 v0, v52, v53 offset1:1
	v_add_u32_e32 v0, 0x34d8, v93
	ds_write2_b32 v0, v54, v55 offset1:1
	v_add_u32_e32 v0, 0x38e0, v93
	s_waitcnt vmcnt(1)
	ds_write2_b32 v0, v56, v57 offset1:1
	v_add_u32_e32 v0, 0x38e8, v93
	ds_write2_b32 v0, v58, v59 offset1:1
	v_add_u32_e32 v0, 0x3cf0, v93
	s_waitcnt vmcnt(0)
	ds_write2_b32 v0, v60, v61 offset1:1
	v_add_u32_e32 v0, 0x3cf8, v93
	ds_write2_b32 v0, v62, v63 offset1:1
	ds_read2_b32 v[4:5], v95 offset0:65 offset1:73
	ds_read2_b32 v[6:7], v95 offset1:8
	ds_read2_b32 v[8:9], v95 offset0:130 offset1:138
	ds_read2_b32 v[10:11], v95 offset0:195 offset1:203
	v_add_u32_e32 v24, 0x400, v95
	ds_read2_b32 v[12:13], v24 offset0:4 offset1:12
	ds_read2_b32 v[14:15], v24 offset0:69 offset1:77
	ds_read2_b32 v[16:17], v24 offset0:134 offset1:142
	ds_read2_b32 v[18:19], v24 offset0:199 offset1:207
	s_mov_b32 s7, s75
	s_waitcnt lgkmcnt(6)
	v_cvt_pk_bf16_f32 v0, v6, v4
	v_or_b32_e32 v4, s8, v94
	v_lshl_add_u64 v[20:21], s[6:7], 1, v[72:73]
	v_lshlrev_b32_e32 v144, 12, v4
	v_lshl_add_u64 v[22:23], v[20:21], 0, v[144:145]
	s_waitcnt lgkmcnt(4)
	v_cvt_pk_bf16_f32 v1, v8, v10
	s_waitcnt lgkmcnt(2)
	v_cvt_pk_bf16_f32 v2, v12, v14
	s_waitcnt lgkmcnt(0)
	v_cvt_pk_bf16_f32 v3, v16, v18
	global_store_dwordx4 v[22:23], v[0:3], off
	v_or_b32_e32 v4, s8, v96
	v_lshlrev_b32_e32 v144, 12, v4
	v_cvt_pk_bf16_f32 v0, v7, v5
	v_cvt_pk_bf16_f32 v1, v9, v11
	v_cvt_pk_bf16_f32 v2, v13, v15
	v_cvt_pk_bf16_f32 v3, v17, v19
	ds_read2_b32 v[6:7], v95 offset0:16 offset1:24
	ds_read2_b32 v[8:9], v95 offset0:81 offset1:89
	ds_read2_b32 v[10:11], v95 offset0:146 offset1:154
	ds_read2_b32 v[12:13], v95 offset0:211 offset1:219
	ds_read2_b32 v[14:15], v24 offset0:20 offset1:28
	ds_read2_b32 v[16:17], v24 offset0:85 offset1:93
	ds_read2_b32 v[18:19], v24 offset0:150 offset1:158
	ds_read2_b32 v[22:23], v24 offset0:215 offset1:223
	v_lshl_add_u64 v[4:5], v[20:21], 0, v[144:145]
	global_store_dwordx4 v[4:5], v[0:3], off
	v_or_b32_e32 v4, s8, v97
	v_lshlrev_b32_e32 v144, 12, v4
	v_lshl_add_u64 v[4:5], v[20:21], 0, v[144:145]
	s_waitcnt lgkmcnt(6)
	v_cvt_pk_bf16_f32 v0, v6, v8
	s_waitcnt lgkmcnt(4)
	v_cvt_pk_bf16_f32 v1, v10, v12
	s_waitcnt lgkmcnt(2)
	v_cvt_pk_bf16_f32 v2, v14, v16
	s_waitcnt lgkmcnt(0)
	v_cvt_pk_bf16_f32 v3, v18, v22
	global_store_dwordx4 v[4:5], v[0:3], off
	v_or_b32_e32 v4, s8, v98
	v_lshlrev_b32_e32 v144, 12, v4
	v_cvt_pk_bf16_f32 v0, v7, v9
	v_cvt_pk_bf16_f32 v1, v11, v13
	v_cvt_pk_bf16_f32 v2, v15, v17
	v_cvt_pk_bf16_f32 v3, v19, v23
	ds_read2_b32 v[6:7], v95 offset0:32 offset1:40
	ds_read2_b32 v[8:9], v95 offset0:97 offset1:105
	ds_read2_b32 v[10:11], v95 offset0:162 offset1:170
	ds_read2_b32 v[12:13], v95 offset0:227 offset1:235
	ds_read2_b32 v[14:15], v24 offset0:36 offset1:44
	ds_read2_b32 v[16:17], v24 offset0:101 offset1:109
	ds_read2_b32 v[18:19], v24 offset0:166 offset1:174
	ds_read2_b32 v[22:23], v24 offset0:231 offset1:239
	v_lshl_add_u64 v[4:5], v[20:21], 0, v[144:145]
	global_store_dwordx4 v[4:5], v[0:3], off
	v_or_b32_e32 v4, s8, v99
	v_lshlrev_b32_e32 v144, 12, v4
	v_lshl_add_u64 v[4:5], v[20:21], 0, v[144:145]
	s_waitcnt lgkmcnt(6)
	v_cvt_pk_bf16_f32 v0, v6, v8
	s_waitcnt lgkmcnt(4)
	v_cvt_pk_bf16_f32 v1, v10, v12
	s_waitcnt lgkmcnt(2)
	v_cvt_pk_bf16_f32 v2, v14, v16
	s_waitcnt lgkmcnt(0)
	v_cvt_pk_bf16_f32 v3, v18, v22
	global_store_dwordx4 v[4:5], v[0:3], off
	v_or_b32_e32 v4, s8, v100
	v_lshlrev_b32_e32 v144, 12, v4
	v_cvt_pk_bf16_f32 v0, v7, v9
	v_cvt_pk_bf16_f32 v1, v11, v13
	v_cvt_pk_bf16_f32 v2, v15, v17
	v_cvt_pk_bf16_f32 v3, v19, v23
	ds_read2_b32 v[6:7], v95 offset0:48 offset1:56
	ds_read2_b32 v[8:9], v95 offset0:113 offset1:121
	ds_read2_b32 v[10:11], v95 offset0:178 offset1:186
	ds_read2_b32 v[12:13], v95 offset0:243 offset1:251
	ds_read2_b32 v[14:15], v24 offset0:52 offset1:60
	ds_read2_b32 v[16:17], v24 offset0:117 offset1:125
	ds_read2_b32 v[18:19], v24 offset0:182 offset1:190
	ds_read2_b32 v[22:23], v24 offset0:247 offset1:255
	v_lshl_add_u64 v[4:5], v[20:21], 0, v[144:145]
	global_store_dwordx4 v[4:5], v[0:3], off
	v_or_b32_e32 v4, s8, v101
	v_lshlrev_b32_e32 v144, 12, v4
	v_lshl_add_u64 v[4:5], v[20:21], 0, v[144:145]
	s_waitcnt lgkmcnt(6)
	v_cvt_pk_bf16_f32 v0, v6, v8
	s_waitcnt lgkmcnt(4)
	v_cvt_pk_bf16_f32 v1, v10, v12
	s_waitcnt lgkmcnt(2)
	v_cvt_pk_bf16_f32 v2, v14, v16
	s_waitcnt lgkmcnt(0)
	v_cvt_pk_bf16_f32 v3, v18, v22
	global_store_dwordx4 v[4:5], v[0:3], off
	v_or_b32_e32 v4, s8, v102
	v_lshlrev_b32_e32 v144, 12, v4
	v_lshl_add_u64 v[4:5], v[20:21], 0, v[144:145]
	v_cvt_pk_bf16_f32 v0, v7, v9
	v_cvt_pk_bf16_f32 v1, v11, v13
	v_cvt_pk_bf16_f32 v2, v15, v17
	v_cvt_pk_bf16_f32 v3, v19, v23
	global_store_dwordx4 v[4:5], v[0:3], off
	s_mov_b64 s[6:7], 0
